# mode-1 scan: rank-2 state update moved to v_mfma_f32_4x4x1_16b_f32 (exact f32 fma), dots stay on VALU
# speedup vs baseline: 1.0048x; 1.0048x over previous
; template <int MODE> __device__ __forceinline__ void rwkv_item(const Params& P, int e, int c, int h, LAS float* slab, int lane) {
;     ...
;             if (NB == 2) RW_LD_DOT(0, 0);
;             const float v = st[320 + lane];
; #pragma unroll
;             for (int hb = 0; hb < NDB; ++hb) {
;                 if (NB == 2) { if (hb + 1 < NDB) RW_LD_DOT((hb + 1) & 1, hb + 1); else RW_LD_UPD(0, 0); } else RW_LD_DOT(0, hb);
;                 __builtin_amdgcn_sched_barrier(0);
; #pragma unroll
;                 for (int q = 0; q < DB; ++q) {
;                     const int qq = DB * hb + q; const f32x4 k4 = kd[hb & (NB - 1)][q];
;                     aS0 += S2[2 * qq] * (f32x2){k4.x, k4.y}; aS1 += S2[2 * qq + 1] * (f32x2){k4.z, k4.w};
;                     if (MODE == 0) { aC0 += C2[2 * qq] * (f32x2){k4.x, k4.y}; aC1 += C2[2 * qq + 1] * (f32x2){k4.z, k4.w}; }
;                 }
;                 __builtin_amdgcn_sched_barrier(0);
;             }
;             const float nsk = -((aS0.x + aS0.y) + (aS1.x + aS1.y));
;             const float nskC = -((aC0.x + aC0.y) + (aC1.x + aC1.y));
;             f32x2 y0 = {0.f, 0.f}, y1 = {0.f, 0.f};
; #pragma unroll
;             for (int qb = 0; qb < NUB; ++qb) {
;                 if (NB == 2) { if (qb + 1 < NUB) RW_LD_UPD((qb + 1) & 1, qb + 1); } else RW_LD_UPD(0, qb);
;                 __builtin_amdgcn_sched_barrier(0);
; #pragma unroll
;                 for (int q = 0; q < UB; ++q) {
;                     const int qq = UB * qb + q;
;                     const f32x4 w4 = wq[qb & (NB - 1)][q], b4 = bq[qb & (NB - 1)][q], k4 = kq[qb & (NB - 1)][q];
;                     if (MODE == 0) {
;                         S2[2 * qq] = S2[2 * qq] * (f32x2){w4.x, w4.y} + (f32x2){b4.x, b4.y} * nsk;
;                         S2[2 * qq + 1] = S2[2 * qq + 1] * (f32x2){w4.z, w4.w} + (f32x2){b4.z, b4.w} * nsk;
;                         C2[2 * qq] = C2[2 * qq] * (f32x2){w4.x, w4.y} + (f32x2){b4.x, b4.y} * nskC + (f32x2){k4.x, k4.y} * v;
;                         C2[2 * qq + 1] = C2[2 * qq + 1] * (f32x2){w4.z, w4.w} + (f32x2){b4.z, b4.w} * nskC + (f32x2){k4.z, k4.w} * v;
;                     } else {
;                         S2[2 * qq] = S2[2 * qq] * (f32x2){w4.x, w4.y} + (f32x2){b4.x, b4.y} * nsk + (f32x2){k4.x, k4.y} * v;
.Lm1_step:
	s_add_i32 s8, s3, s11
	v_add_u32_e32 v197, s11, v109
	v_and_b32_e32 v199, 3, v64
	v_mov_b32_e32 v196, s8
	v_lshl_add_u32 v199, v199, 2, s8
	ds_read_b32 v194, v197 offset:1280
	ds_read_b128 v[136:139], v196 offset:256
	ds_read_b128 v[140:143], v196 offset:272
	ds_read_b128 v[144:147], v196 offset:288
	ds_read_b128 v[148:151], v196 offset:304
	ds_read_b128 v[176:179], v196 offset:320
	ds_read_b128 v[180:183], v196 offset:336
	ds_read_b128 v[184:187], v196 offset:352
	ds_read_b128 v[188:191], v196 offset:368
	s_waitcnt lgkmcnt(7)
	v_pk_fma_f32 v[158:159], v[0:1], v[136:137], 0 op_sel_hi:[1,1,0]
	v_pk_fma_f32 v[160:161], v[2:3], v[138:139], 0 op_sel_hi:[1,1,0]
	ds_read_b128 v[136:139], v196 offset:384
	s_waitcnt lgkmcnt(7)
	v_pk_fma_f32 v[158:159], v[4:5], v[140:141], v[158:159]
	v_pk_fma_f32 v[160:161], v[6:7], v[142:143], v[160:161]
	ds_read_b128 v[140:143], v196 offset:400
	s_waitcnt lgkmcnt(7)
	v_pk_fma_f32 v[158:159], v[8:9], v[144:145], v[158:159]
	v_pk_fma_f32 v[160:161], v[10:11], v[146:147], v[160:161]
	ds_read_b128 v[144:147], v196 offset:416
	s_waitcnt lgkmcnt(7)
	v_pk_fma_f32 v[158:159], v[12:13], v[148:149], v[158:159]
	v_pk_fma_f32 v[160:161], v[14:15], v[150:151], v[160:161]
	ds_read_b128 v[148:151], v196 offset:432
	s_waitcnt lgkmcnt(7)
	v_pk_fma_f32 v[158:159], v[16:17], v[176:177], v[158:159]
	v_pk_fma_f32 v[160:161], v[18:19], v[178:179], v[160:161]
	ds_read_b128 v[176:179], v196 offset:448
	s_waitcnt lgkmcnt(7)
	v_pk_fma_f32 v[158:159], v[20:21], v[180:181], v[158:159]
	v_pk_fma_f32 v[160:161], v[22:23], v[182:183], v[160:161]
	ds_read_b128 v[180:183], v196 offset:464
	s_waitcnt lgkmcnt(7)
	v_pk_fma_f32 v[158:159], v[24:25], v[184:185], v[158:159]
	v_pk_fma_f32 v[160:161], v[26:27], v[186:187], v[160:161]
	ds_read_b128 v[184:187], v196 offset:480
	s_waitcnt lgkmcnt(7)
	v_pk_fma_f32 v[158:159], v[28:29], v[188:189], v[158:159]
	v_pk_fma_f32 v[160:161], v[30:31], v[190:191], v[160:161]
	ds_read_b128 v[188:191], v196 offset:496
	s_waitcnt lgkmcnt(7)
	v_pk_fma_f32 v[158:159], v[32:33], v[136:137], v[158:159]
	v_pk_fma_f32 v[160:161], v[34:35], v[138:139], v[160:161]
	ds_read_b32 v124, v199 offset:512
	s_waitcnt lgkmcnt(7)
	v_pk_fma_f32 v[158:159], v[36:37], v[140:141], v[158:159]
	v_pk_fma_f32 v[160:161], v[38:39], v[142:143], v[160:161]
	ds_read_b32 v125, v199 offset:528
	s_waitcnt lgkmcnt(7)
	v_pk_fma_f32 v[158:159], v[40:41], v[144:145], v[158:159]
	v_pk_fma_f32 v[160:161], v[42:43], v[146:147], v[160:161]
	ds_read_b32 v126, v199 offset:544
	s_waitcnt lgkmcnt(7)
	v_pk_fma_f32 v[158:159], v[44:45], v[148:149], v[158:159]
	v_pk_fma_f32 v[160:161], v[46:47], v[150:151], v[160:161]
	ds_read_b32 v127, v199 offset:560
	s_waitcnt lgkmcnt(7)
	v_pk_fma_f32 v[158:159], v[48:49], v[176:177], v[158:159]
	v_pk_fma_f32 v[160:161], v[50:51], v[178:179], v[160:161]
	ds_read_b32 v128, v199 offset:576
	s_waitcnt lgkmcnt(7)
	v_pk_fma_f32 v[158:159], v[52:53], v[180:181], v[158:159]
	v_pk_fma_f32 v[160:161], v[54:55], v[182:183], v[160:161]
	ds_read_b32 v129, v199 offset:592
	s_waitcnt lgkmcnt(7)
	v_pk_fma_f32 v[158:159], v[56:57], v[184:185], v[158:159]
	v_pk_fma_f32 v[160:161], v[58:59], v[186:187], v[160:161]
	ds_read_b32 v130, v199 offset:608
	s_waitcnt lgkmcnt(7)
	v_pk_fma_f32 v[158:159], v[60:61], v[188:189], v[158:159]
	v_pk_fma_f32 v[160:161], v[62:63], v[190:191], v[160:161]
	ds_read_b32 v131, v199 offset:624
	v_add_f32_e32 v192, v158, v159
	v_add_f32_e32 v198, v160, v161
	v_add_f32_e32 v192, v198, v192
	v_mul_f32_e32 v193, -1.0, v192
	s_nop 1
	s_waitcnt lgkmcnt(7)
	v_mfma_f32_4x4x1_16b_f32 v[0:3], v124, v193, v[0:3]
	ds_read_b32 v124, v199 offset:640
	s_waitcnt lgkmcnt(7)
	v_mfma_f32_4x4x1_16b_f32 v[4:7], v125, v193, v[4:7]
	ds_read_b32 v125, v199 offset:656
	s_waitcnt lgkmcnt(7)
	v_mfma_f32_4x4x1_16b_f32 v[8:11], v126, v193, v[8:11]
	ds_read_b32 v126, v199 offset:672
	s_waitcnt lgkmcnt(7)
	v_mfma_f32_4x4x1_16b_f32 v[12:15], v127, v193, v[12:15]
	ds_read_b32 v127, v199 offset:688
	s_waitcnt lgkmcnt(7)
	v_mfma_f32_4x4x1_16b_f32 v[16:19], v128, v193, v[16:19]
	ds_read_b32 v128, v199 offset:704
	s_waitcnt lgkmcnt(7)
	v_mfma_f32_4x4x1_16b_f32 v[20:23], v129, v193, v[20:23]
	ds_read_b32 v129, v199 offset:720
	s_waitcnt lgkmcnt(7)
	v_mfma_f32_4x4x1_16b_f32 v[24:27], v130, v193, v[24:27]
	ds_read_b32 v130, v199 offset:736
	s_waitcnt lgkmcnt(7)
	v_mfma_f32_4x4x1_16b_f32 v[28:31], v131, v193, v[28:31]
	ds_read_b32 v131, v199 offset:752
	s_waitcnt lgkmcnt(7)
	v_mfma_f32_4x4x1_16b_f32 v[32:35], v124, v193, v[32:35]
	ds_read_b32 v124, v199 offset:768
	s_waitcnt lgkmcnt(7)
	v_mfma_f32_4x4x1_16b_f32 v[36:39], v125, v193, v[36:39]
	ds_read_b32 v125, v199 offset:784
	s_waitcnt lgkmcnt(7)
	v_mfma_f32_4x4x1_16b_f32 v[40:43], v126, v193, v[40:43]
	ds_read_b32 v126, v199 offset:800
	s_waitcnt lgkmcnt(7)
	v_mfma_f32_4x4x1_16b_f32 v[44:47], v127, v193, v[44:47]
	ds_read_b32 v127, v199 offset:816
	s_waitcnt lgkmcnt(7)
	v_mfma_f32_4x4x1_16b_f32 v[48:51], v128, v193, v[48:51]
	ds_read_b32 v128, v199 offset:832
	s_waitcnt lgkmcnt(7)
	v_mfma_f32_4x4x1_16b_f32 v[52:55], v129, v193, v[52:55]
	ds_read_b32 v129, v199 offset:848
	s_waitcnt lgkmcnt(7)
	v_mfma_f32_4x4x1_16b_f32 v[56:59], v130, v193, v[56:59]
	ds_read_b32 v130, v199 offset:864
	s_waitcnt lgkmcnt(7)
	v_mfma_f32_4x4x1_16b_f32 v[60:63], v131, v193, v[60:63]
	ds_read_b32 v131, v199 offset:880
	s_waitcnt lgkmcnt(7)
	v_mfma_f32_4x4x1_16b_f32 v[0:3], v124, v194, v[0:3]
	ds_read_b32 v124, v199 offset:896
	s_waitcnt lgkmcnt(7)
	v_mfma_f32_4x4x1_16b_f32 v[4:7], v125, v194, v[4:7]
	ds_read_b32 v125, v199 offset:912
	s_waitcnt lgkmcnt(7)
	v_mfma_f32_4x4x1_16b_f32 v[8:11], v126, v194, v[8:11]
	ds_read_b32 v126, v199 offset:928
	s_waitcnt lgkmcnt(7)
; #define LAS __attribute__((address_space(3)))
; #define RW_LD_UPD(buf, qb) do { _Pragma("unroll") for (int q_ = 0; q_ < UB; ++q_) { const int qq_ = UB * (qb) + q_; \
;                 wq[buf][q_] = *(const LAS f32x4*)(st + 4 * qq_); bq[buf][q_] = *(const LAS f32x4*)(st + 128 + 4 * qq_); kq[buf][q_] = *(const LAS f32x4*)(st + 192 + 4 * qq_); \
;                 if (MODE == 1) rq[buf][q_] = *(const LAS f32x4*)(st + 256 + 4 * qq_); } } while (0)
; template <int MODE> __device__ __forceinline__ void rwkv_item(const Params& P, int e, int c, int h, LAS float* slab, int lane) {
;     ...
;             for (int qb = 0; qb < NUB; ++qb) {
;                 if (NB == 2) { if (qb + 1 < NUB) RW_LD_UPD((qb + 1) & 1, qb + 1); } else RW_LD_UPD(0, qb);
;                 __builtin_amdgcn_sched_barrier(0);
; #pragma unroll
;                 for (int q = 0; q < UB; ++q) {
;                     const int qq = UB * qb + q;
;                     const f32x4 w4 = wq[qb & (NB - 1)][q], b4 = bq[qb & (NB - 1)][q], k4 = kq[qb & (NB - 1)][q];
;                     if (MODE == 0) {
;                         S2[2 * qq] = S2[2 * qq] * (f32x2){w4.x, w4.y} + (f32x2){b4.x, b4.y} * nsk;
;                         S2[2 * qq + 1] = S2[2 * qq + 1] * (f32x2){w4.z, w4.w} + (f32x2){b4.z, b4.w} * nsk;
;                         C2[2 * qq] = C2[2 * qq] * (f32x2){w4.x, w4.y} + (f32x2){b4.x, b4.y} * nskC + (f32x2){k4.x, k4.y} * v;
;                         C2[2 * qq + 1] = C2[2 * qq + 1] * (f32x2){w4.z, w4.w} + (f32x2){b4.z, b4.w} * nskC + (f32x2){k4.z, k4.w} * v;
;                     } else {
;                         S2[2 * qq] = S2[2 * qq] * (f32x2){w4.x, w4.y} + (f32x2){b4.x, b4.y} * nsk + (f32x2){k4.x, k4.y} * v;
;                         S2[2 * qq + 1] = S2[2 * qq + 1] * (f32x2){w4.z, w4.w} + (f32x2){b4.z, b4.w} * nsk + (f32x2){k4.z, k4.w} * v;
;                         const f32x4 r4 = rq[qb & (NB - 1)][q]; y0 += S2[2 * qq] * (f32x2){r4.x, r4.y}; y1 += S2[2 * qq + 1] * (f32x2){r4.z, r4.w};
;                     }
;                 }
;                 __builtin_amdgcn_sched_barrier(0);
;             }
;     ...
;             if (MODE == 1) ((LAS float*)st)[lane] = (y0.x + y0.y) + (y1.x + y1.y);
	v_mfma_f32_4x4x1_16b_f32 v[12:15], v127, v194, v[12:15]
	ds_read_b32 v127, v199 offset:944
	s_waitcnt lgkmcnt(7)
	v_mfma_f32_4x4x1_16b_f32 v[16:19], v128, v194, v[16:19]
	ds_read_b32 v128, v199 offset:960
	s_waitcnt lgkmcnt(7)
	v_mfma_f32_4x4x1_16b_f32 v[20:23], v129, v194, v[20:23]
	ds_read_b32 v129, v199 offset:976
	s_waitcnt lgkmcnt(7)
	v_mfma_f32_4x4x1_16b_f32 v[24:27], v130, v194, v[24:27]
	ds_read_b32 v130, v199 offset:992
	s_waitcnt lgkmcnt(7)
	v_mfma_f32_4x4x1_16b_f32 v[28:31], v131, v194, v[28:31]
	ds_read_b32 v131, v199 offset:1008
	s_waitcnt lgkmcnt(7)
	v_mfma_f32_4x4x1_16b_f32 v[32:35], v124, v194, v[32:35]
	ds_read_b128 v[136:139], v196 offset:1024
	s_waitcnt lgkmcnt(7)
	v_mfma_f32_4x4x1_16b_f32 v[36:39], v125, v194, v[36:39]
	ds_read_b128 v[140:143], v196 offset:1040
	s_waitcnt lgkmcnt(7)
	v_mfma_f32_4x4x1_16b_f32 v[40:43], v126, v194, v[40:43]
	ds_read_b128 v[144:147], v196 offset:1056
	s_waitcnt lgkmcnt(7)
	v_mfma_f32_4x4x1_16b_f32 v[44:47], v127, v194, v[44:47]
	ds_read_b128 v[148:151], v196 offset:1072
	s_waitcnt lgkmcnt(7)
	v_mfma_f32_4x4x1_16b_f32 v[48:51], v128, v194, v[48:51]
	ds_read_b128 v[176:179], v196 offset:1088
	s_waitcnt lgkmcnt(7)
	v_mfma_f32_4x4x1_16b_f32 v[52:55], v129, v194, v[52:55]
	ds_read_b128 v[180:183], v196 offset:1104
	s_waitcnt lgkmcnt(7)
	v_mfma_f32_4x4x1_16b_f32 v[56:59], v130, v194, v[56:59]
	ds_read_b128 v[184:187], v196 offset:1120
	s_waitcnt lgkmcnt(7)
	v_mfma_f32_4x4x1_16b_f32 v[60:63], v131, v194, v[60:63]
	ds_read_b128 v[188:191], v196 offset:1136
	s_waitcnt lgkmcnt(7)
	v_pk_fma_f32 v[162:163], v[136:137], v[0:1], 0 op_sel_hi:[1,1,0]
	v_pk_fma_f32 v[164:165], v[138:139], v[2:3], 0 op_sel_hi:[1,1,0]
	ds_read_b128 v[136:139], v196 offset:1152
	s_waitcnt lgkmcnt(7)
	v_pk_fma_f32 v[162:163], v[140:141], v[4:5], v[162:163]
	v_pk_fma_f32 v[164:165], v[142:143], v[6:7], v[164:165]
	ds_read_b128 v[140:143], v196 offset:1168
	s_waitcnt lgkmcnt(7)
	v_pk_fma_f32 v[162:163], v[144:145], v[8:9], v[162:163]
	v_pk_fma_f32 v[164:165], v[146:147], v[10:11], v[164:165]
	ds_read_b128 v[144:147], v196 offset:1184
	s_waitcnt lgkmcnt(7)
	v_pk_fma_f32 v[162:163], v[148:149], v[12:13], v[162:163]
	v_pk_fma_f32 v[164:165], v[150:151], v[14:15], v[164:165]
	ds_read_b128 v[148:151], v196 offset:1200
	s_waitcnt lgkmcnt(7)
	v_pk_fma_f32 v[162:163], v[176:177], v[16:17], v[162:163]
	v_pk_fma_f32 v[164:165], v[178:179], v[18:19], v[164:165]
	ds_read_b128 v[176:179], v196 offset:1216
	s_waitcnt lgkmcnt(7)
	v_pk_fma_f32 v[162:163], v[180:181], v[20:21], v[162:163]
	v_pk_fma_f32 v[164:165], v[182:183], v[22:23], v[164:165]
	ds_read_b128 v[180:183], v196 offset:1232
	s_waitcnt lgkmcnt(7)
	v_pk_fma_f32 v[162:163], v[184:185], v[24:25], v[162:163]
	v_pk_fma_f32 v[164:165], v[186:187], v[26:27], v[164:165]
	ds_read_b128 v[184:187], v196 offset:1248
	s_waitcnt lgkmcnt(7)
	v_pk_fma_f32 v[162:163], v[188:189], v[28:29], v[162:163]
	v_pk_fma_f32 v[164:165], v[190:191], v[30:31], v[164:165]
	ds_read_b128 v[188:191], v196 offset:1264
	s_waitcnt lgkmcnt(7)
	v_pk_fma_f32 v[162:163], v[136:137], v[32:33], v[162:163]
	v_pk_fma_f32 v[164:165], v[138:139], v[34:35], v[164:165]
	s_waitcnt lgkmcnt(6)
	v_pk_fma_f32 v[162:163], v[140:141], v[36:37], v[162:163]
	v_pk_fma_f32 v[164:165], v[142:143], v[38:39], v[164:165]
	s_waitcnt lgkmcnt(5)
	v_pk_fma_f32 v[162:163], v[144:145], v[40:41], v[162:163]
	v_pk_fma_f32 v[164:165], v[146:147], v[42:43], v[164:165]
	s_waitcnt lgkmcnt(4)
	v_pk_fma_f32 v[162:163], v[148:149], v[44:45], v[162:163]
	v_pk_fma_f32 v[164:165], v[150:151], v[46:47], v[164:165]
	s_waitcnt lgkmcnt(3)
	v_pk_fma_f32 v[162:163], v[176:177], v[48:49], v[162:163]
	v_pk_fma_f32 v[164:165], v[178:179], v[50:51], v[164:165]
	s_waitcnt lgkmcnt(2)
	v_pk_fma_f32 v[162:163], v[180:181], v[52:53], v[162:163]
	v_pk_fma_f32 v[164:165], v[182:183], v[54:55], v[164:165]
	s_waitcnt lgkmcnt(1)
	v_pk_fma_f32 v[162:163], v[184:185], v[56:57], v[162:163]
	v_pk_fma_f32 v[164:165], v[186:187], v[58:59], v[164:165]
	s_waitcnt lgkmcnt(0)
	v_pk_fma_f32 v[162:163], v[188:189], v[60:61], v[162:163]
	v_pk_fma_f32 v[164:165], v[190:191], v[62:63], v[164:165]
	v_add_f32_e32 v198, v162, v163
	v_add_f32_e32 v192, v164, v165
	v_add_f32_e32 v198, v192, v198
	s_addk_i32 s11, 0x800
	ds_write_b32 v197, v198
	s_cmpk_eq_i32 s11, 0x4000
	s_cbranch_scc0 .Lm1_step
; #define LAS __attribute__((address_space(3)))
; __device__ __forceinline__ unsigned f2bf(float f) { unsigned u = __float_as_uint(f); return (u + 0x7fffu + ((u >> 16) & 1u)) >> 16; }
; __device__ __forceinline__ float frsq(float x) { return __builtin_amdgcn_rsqf(x); }
; #define LDS_WAIT() asm volatile("s_waitcnt lgkmcnt(0)" ::: "memory")
; template <int MODE> __device__ __forceinline__ void rwkv_item(const Params& P, int e, int c, int h, LAS float* slab, int lane) {
;     ...
;         if (MODE == 1) {
;             LDS_WAIT();
; #pragma unroll
;             for (int s = 0; s < SB; ++s) {
;                 const LAS float* st = slab + s * 512;
;                 const float y = st[lane], v = st[320 + lane];
;                 const float mean = wave_sum(y) * (1.f / 64.f), d = y - mean;
;                 const float var = wave_sum(d * d) * (1.f / 64.f);
;                 const float yn = d * frsq(var + 64e-5f) * lnw + lnb;
;                 MIX[(size_t)(tb + s) * D + ch] = (bf16)f2bf((yn + st[384 + lane] * v) * st[448 + lane]);
;             }
;         }
;         LDS_WAIT();
	s_waitcnt lgkmcnt(0)
	s_waitcnt vmcnt(48)
	ds_read_b128 v[192:195], v175
	ds_read_b128 v[196:199], v175 offset:16
	ds_read2st64_b32 v[136:137], v109 offset0:0 offset1:5
	ds_read2st64_b32 v[138:139], v109 offset0:8 offset1:13
	ds_read2st64_b32 v[140:141], v109 offset0:16 offset1:21
	ds_read2st64_b32 v[142:143], v109 offset0:24 offset1:29
	ds_read2st64_b32 v[144:145], v109 offset0:32 offset1:37
	ds_read2st64_b32 v[146:147], v109 offset0:40 offset1:45
	ds_read2st64_b32 v[148:149], v109 offset0:48 offset1:53
	ds_read2st64_b32 v[150:151], v109 offset0:56 offset1:61
	s_waitcnt lgkmcnt(8)
	v_add_f32_e32 v192, v192, v193
	v_add_f32_e32 v194, v194, v195
	v_add_f32_e32 v196, v196, v197
	v_add_f32_e32 v198, v198, v199
	v_add_f32_e32 v192, v192, v194
	v_add_f32_e32 v196, v196, v198
	v_add_f32_e32 v192, v192, v196
	s_nop 1
	v_add_f32_dpp v192, v192, v192 quad_perm:[1,0,3,2] row_mask:0xf bank_mask:0xf bound_ctrl:1
	s_nop 1
	v_add_f32_dpp v192, v192, v192 quad_perm:[2,3,0,1] row_mask:0xf bank_mask:0xf bound_ctrl:1
	s_nop 1
	v_add_f32_dpp v192, v192, v192 row_half_mirror row_mask:0xf bank_mask:0xf bound_ctrl:1
	ds_write_b32 v208, v192
	s_waitcnt lgkmcnt(0)
	ds_read_b128 v[184:187], v209
	ds_read_b128 v[188:191], v209 offset:16
	s_waitcnt lgkmcnt(0)
	v_fmamk_f32 v136, v184, 0xbc800000, v136
	v_mul_f32_e32 v124, v136, v136
	ds_write_b32 v109, v124
	v_fmamk_f32 v138, v185, 0xbc800000, v138
	v_mul_f32_e32 v124, v138, v138
	ds_write_b32 v109, v124 offset:2048
	v_fmamk_f32 v140, v186, 0xbc800000, v140
	v_mul_f32_e32 v124, v140, v140
	ds_write_b32 v109, v124 offset:4096
	v_fmamk_f32 v142, v187, 0xbc800000, v142
	v_mul_f32_e32 v124, v142, v142
	ds_write_b32 v109, v124 offset:6144
	v_fmamk_f32 v144, v188, 0xbc800000, v144
	v_mul_f32_e32 v124, v144, v144
	ds_write_b32 v109, v124 offset:8192
	v_fmamk_f32 v146, v189, 0xbc800000, v146
	v_mul_f32_e32 v124, v146, v146
	ds_write_b32 v109, v124 offset:10240
	v_fmamk_f32 v148, v190, 0xbc800000, v148
	v_mul_f32_e32 v124, v148, v148
	ds_write_b32 v109, v124 offset:12288
	v_fmamk_f32 v150, v191, 0xbc800000, v150
	v_mul_f32_e32 v124, v150, v150
	ds_write_b32 v109, v124 offset:14336
	s_waitcnt lgkmcnt(0)
	ds_read_b128 v[192:195], v175
	ds_read_b128 v[196:199], v175 offset:16
	s_waitcnt lgkmcnt(0)
	v_add_f32_e32 v192, v192, v193
	v_add_f32_e32 v194, v194, v195
	v_add_f32_e32 v196, v196, v197
	v_add_f32_e32 v198, v198, v199
	v_add_f32_e32 v192, v192, v194
	v_add_f32_e32 v196, v196, v198
	v_add_f32_e32 v192, v192, v196
	s_nop 1
	v_add_f32_dpp v192, v192, v192 quad_perm:[1,0,3,2] row_mask:0xf bank_mask:0xf bound_ctrl:1
	s_nop 1
	v_add_f32_dpp v192, v192, v192 quad_perm:[2,3,0,1] row_mask:0xf bank_mask:0xf bound_ctrl:1
	s_nop 1
	v_add_f32_dpp v192, v192, v192 row_half_mirror row_mask:0xf bank_mask:0xf bound_ctrl:1
	ds_write_b32 v208, v192
	s_waitcnt lgkmcnt(0)
	ds_read_b128 v[184:187], v209
	ds_read_b128 v[188:191], v209 offset:16
	ds_read2st64_b32 v[128:129], v109 offset0:6 offset1:7
	ds_read2st64_b32 v[130:131], v109 offset0:14 offset1:15
	ds_read2st64_b32 v[132:133], v109 offset0:22 offset1:23
	ds_read2st64_b32 v[134:135], v109 offset0:30 offset1:31
	ds_read2st64_b32 v[192:193], v109 offset0:38 offset1:39
	ds_read2st64_b32 v[194:195], v109 offset0:46 offset1:47
	ds_read2st64_b32 v[196:197], v109 offset0:54 offset1:55
	ds_read2st64_b32 v[198:199], v109 offset0:62 offset1:63
	s_waitcnt lgkmcnt(7)
	v_fmamk_f32 v124, v184, 0x3c800000, v221
	v_rsq_f32_e32 v124, v124
	v_add_u32_e32 v127, 0x0, v113
	v_mul_f32_e32 v136, v136, v124
	v_fma_f32 v136, v120, v136, v121
	v_fmac_f32_e32 v136, v137, v128
	v_mul_f32_e32 v136, v129, v136
	v_bfe_u32 v125, v136, 16, 1
	v_add3_u32 v126, v136, v125, s33
	global_store_short_d16_hi v127, v126, s[70:71]
	s_waitcnt lgkmcnt(6)
	v_fmamk_f32 v124, v185, 0x3c800000, v221
	v_rsq_f32_e32 v124, v124
	v_add_u32_e32 v127, 0x800, v113
	v_mul_f32_e32 v138, v138, v124
	v_fma_f32 v138, v120, v138, v121
	v_fmac_f32_e32 v138, v139, v130
	v_mul_f32_e32 v138, v131, v138
	v_bfe_u32 v125, v138, 16, 1
	v_add3_u32 v126, v138, v125, s33
	global_store_short_d16_hi v127, v126, s[70:71]
	s_waitcnt lgkmcnt(5)
	v_fmamk_f32 v124, v186, 0x3c800000, v221
	v_rsq_f32_e32 v124, v124
	v_add_u32_e32 v127, 0x1000, v113
	v_mul_f32_e32 v140, v140, v124
	v_fma_f32 v140, v120, v140, v121
	v_fmac_f32_e32 v140, v141, v132
	v_mul_f32_e32 v140, v133, v140
	v_bfe_u32 v125, v140, 16, 1
	v_add3_u32 v126, v140, v125, s33
	global_store_short_d16_hi v127, v126, s[70:71]
	s_waitcnt lgkmcnt(4)
	v_fmamk_f32 v124, v187, 0x3c800000, v221
	v_rsq_f32_e32 v124, v124
	v_add_u32_e32 v127, 0x1800, v113
	v_mul_f32_e32 v142, v142, v124
	v_fma_f32 v142, v120, v142, v121
	v_fmac_f32_e32 v142, v143, v134
	v_mul_f32_e32 v142, v135, v142
	v_bfe_u32 v125, v142, 16, 1
	v_add3_u32 v126, v142, v125, s33
	global_store_short_d16_hi v127, v126, s[70:71]
	s_waitcnt lgkmcnt(3)
	v_fmamk_f32 v124, v188, 0x3c800000, v221
	v_rsq_f32_e32 v124, v124
	v_add_u32_e32 v127, 0x2000, v113
	v_mul_f32_e32 v144, v144, v124
	v_fma_f32 v144, v120, v144, v121
	v_fmac_f32_e32 v144, v145, v192
	v_mul_f32_e32 v144, v193, v144
	v_bfe_u32 v125, v144, 16, 1
	v_add3_u32 v126, v144, v125, s33
	global_store_short_d16_hi v127, v126, s[70:71]
	s_waitcnt lgkmcnt(2)
	v_fmamk_f32 v124, v189, 0x3c800000, v221
	v_rsq_f32_e32 v124, v124
	v_add_u32_e32 v127, 0x2800, v113
	v_mul_f32_e32 v146, v146, v124
	v_fma_f32 v146, v120, v146, v121
	v_fmac_f32_e32 v146, v147, v194
	v_mul_f32_e32 v146, v195, v146
	v_bfe_u32 v125, v146, 16, 1
	v_add3_u32 v126, v146, v125, s33
	global_store_short_d16_hi v127, v126, s[70:71]
	s_waitcnt lgkmcnt(1)
	v_fmamk_f32 v124, v190, 0x3c800000, v221
	v_rsq_f32_e32 v124, v124
	v_add_u32_e32 v127, 0x3000, v113
	v_mul_f32_e32 v148, v148, v124
	v_fma_f32 v148, v120, v148, v121
	v_fmac_f32_e32 v148, v149, v196
	v_mul_f32_e32 v148, v197, v148
	v_bfe_u32 v125, v148, 16, 1
	v_add3_u32 v126, v148, v125, s33
	global_store_short_d16_hi v127, v126, s[70:71]
	s_waitcnt lgkmcnt(0)
	v_fmamk_f32 v124, v191, 0x3c800000, v221
	v_rsq_f32_e32 v124, v124
	v_add_u32_e32 v127, 0x3800, v113
	v_mul_f32_e32 v150, v150, v124
	v_fma_f32 v150, v120, v150, v121
	v_fmac_f32_e32 v150, v151, v198
	v_mul_f32_e32 v150, v199, v150
	v_bfe_u32 v125, v150, 16, 1
	v_add3_u32 v126, v150, v125, s33
	global_store_short_d16_hi v127, v126, s[70:71]
	v_add_u32_e32 v113, 0x4000, v113
	s_add_i32 s1, s1, 1
	s_cmp_eq_u32 s1, 8
	s_cbranch_scc0 .Lm1_sub
	s_add_i32 s2, s2, s58
	s_cmpk_gt_i32 s2, 0x7ff
	s_cbranch_scc0 .LBB0_205
	s_load_dwordx2 s[72:73], s[30:31], 0x118
	v_readlane_b32 s12, v253, 17
	v_readlane_b32 s13, v253, 18
	v_readlane_b32 s67, v255, 14
	v_readlane_b32 s71, v255, 15
	v_readlane_b32 s51, v255, 16
